# LayerNorm row loops: counted vmcnt at the loop head (covers only the row prefetch, not the acknowledgement of the previous row's stores); preheader drains once
# speedup vs baseline: 1.0134x; 1.0134x over previous
.LBB0_1219:
	s_or_b64 exec, exec, s[0:1]
	s_waitcnt lgkmcnt(0)
	v_mov_b32_e32 v0, v196
	v_readlane_b32 s8, v253, 27
	s_barrier
	v_readlane_b32 s9, v253, 28
	v_readlane_b32 s10, v253, 29
	v_readlane_b32 s11, v253, 30
	v_and_b32_e32 v49, 63, v0
	v_readfirstlane_b32 s3, v0
	v_mov_b32_e32 v0, s10
	v_mov_b32_e32 v1, s11
	v_readlane_b32 s6, v255, 0
	v_readlane_b32 s8, v255, 2
	v_mov_b32_e32 v48, s94
	v_mov_b32_e32 v50, s95
	v_lshlrev_b32_e32 v144, 4, v49
	v_readlane_b32 s7, v255, 1
	v_readlane_b32 s9, v255, 3
	v_readfirstlane_b32 s0, v0
	v_readfirstlane_b32 s1, v1
	s_nop 1
	global_load_dwordx4 v[0:3], v144, s[6:7]
	global_load_dwordx4 v[4:7], v144, s[6:7] offset:1024
	global_load_dwordx4 v[8:11], v144, s[8:9]
	global_load_dwordx4 v[12:15], v144, s[8:9] offset:1024
	global_load_dwordx4 v[16:19], v144, s[6:7] offset:2048
	global_load_dwordx4 v[20:23], v144, s[6:7] offset:3072
	global_load_dwordx4 v[24:27], v144, s[8:9] offset:2048
	global_load_dwordx4 v[28:31], v144, s[8:9] offset:3072
	s_ashr_i32 s3, s3, 6
	v_readlane_b32 s6, v253, 53
	s_add_i32 s10, s6, s3
	s_ashr_i32 s11, s10, 31
	s_add_i32 s18, s3, s88
	s_lshl_b64 s[6:7], s[10:11], 12
	s_add_u32 s6, s0, s6
	s_addc_u32 s7, s1, s7
	v_lshl_add_u64 v[32:33], s[6:7], 0, v[144:145]
	s_mov_b32 s3, 0x100000
	global_load_dwordx4 v[108:111], v144, s[6:7]
	global_load_dwordx4 v[104:107], v144, s[6:7] offset:1024
	global_load_dwordx4 v[100:103], v144, s[6:7] offset:2048
	global_load_dwordx4 v[88:91], v144, s[6:7] offset:3072
	s_mov_b64 s[6:7], 0x100000
	v_add_co_u32_e32 v36, vcc, s3, v32
	v_lshl_add_u64 v[44:45], v[32:33], 0, s[6:7]
	s_nop 0
	v_addc_co_u32_e32 v37, vcc, 0, v33, vcc
	global_load_dwordx4 v[32:35], v[44:45], off offset:1024
	global_load_dwordx4 v[40:43], v[44:45], off offset:2048
	s_nop 0
	global_load_dwordx4 v[36:39], v[36:37], off
	s_nop 0
	global_load_dwordx4 v[44:47], v[44:45], off offset:3072
	s_cmpk_lt_i32 s18, 0x200
	v_readfirstlane_b32 s8, v48
	s_cselect_b32 s11, 9, 8
	s_addk_i32 s18, 0x4000
	v_and_b32_e32 v53, 64, v220
	v_readfirstlane_b32 s9, v50
	s_add_u32 s19, s8, 0x306000
	v_xor_b32_e32 v51, 16, v220
	v_add_u32_e32 v53, 64, v53
	s_addc_u32 s20, s9, 0
	v_cmp_lt_i32_e32 vcc, v51, v53
	s_add_u32 s21, s8, 0x10800000
	s_addc_u32 s22, s9, 0
	v_cndmask_b32_e32 v51, v220, v51, vcc
	v_lshlrev_b32_e32 v151, 2, v51
	v_xor_b32_e32 v51, 32, v220
	v_lshlrev_b32_e32 v48, 2, v49
	v_cmp_lt_i32_e32 vcc, v51, v53
	s_add_u32 s23, s8, 0x280000
	v_lshl_add_u64 v[154:155], s[0:1], 0, v[144:145]
	v_lshlrev_b32_e32 v144, 3, v49
	v_or_b32_e32 v50, 0x100, v48
	v_or_b32_e32 v52, 0x200, v48
	v_or_b32_e32 v54, 0x300, v48
	v_cndmask_b32_e32 v51, v220, v51, vcc
	s_addc_u32 s24, s9, 0
	v_lshl_add_u64 v[56:57], s[8:9], 0, v[144:145]
	s_mov_b64 s[8:9], 0x6300000
	s_mov_b32 s3, 0
	v_lshlrev_b32_e32 v158, 2, v51
	v_cmp_eq_u32_e64 s[6:7], 0, v49
	v_lshl_add_u64 v[156:157], v[56:57], 0, s[8:9]
	v_lshlrev_b32_e32 v144, 2, v48
	v_lshlrev_b32_e32 v159, 2, v50
	v_lshlrev_b32_e32 v160, 2, v52
	v_lshlrev_b32_e32 v161, 2, v54
	s_waitcnt vmcnt(0)
	s_branch .LBB0_1221

.LBB0_1221:
	s_cmp_lt_u32 s3, 8
	s_cselect_b32 s12, s10, s18
	s_add_i32 s92, s12, 0xffffc000
	s_lshr_b32 s9, s92, 2
	s_ashr_i32 s8, s12, 11
	s_add_i32 s9, s9, 8
	s_cmpk_lt_i32 s12, 0x4000
	s_cselect_b32 s8, s8, s9
	v_readlane_b32 s9, v255, 4
	s_add_i32 s8, s8, s9
	s_mul_hi_i32 s9, s8, 0x9000
	s_mul_i32 s8, s8, 0x9000
	s_add_u32 s8, s19, s8
	s_addc_u32 s9, s20, s9
	s_add_u32 s14, s8, 0x1000
	s_addc_u32 s15, s9, 0
	global_load_dwordx4 v[92:95], v144, s[8:9]
	global_load_dwordx4 v[80:83], v144, s[8:9] offset:1024
	global_load_dwordx4 v[96:99], v144, s[14:15]
	global_load_dwordx4 v[84:87], v159, s[14:15]
	global_load_dwordx4 v[72:75], v144, s[8:9] offset:2048
	global_load_dwordx4 v[64:67], v144, s[8:9] offset:3072
	global_load_dwordx4 v[76:79], v160, s[14:15]
	global_load_dwordx4 v[68:71], v161, s[14:15]
	s_waitcnt vmcnt(12)
	v_mov_b64_e32 v[50:51], v[46:47]
	v_mov_b64_e32 v[54:55], v[42:43]
	v_mov_b64_e32 v[58:59], v[34:35]
	s_add_i32 s8, s3, 2
	v_mov_b64_e32 v[62:63], v[38:39]
	v_mov_b64_e32 v[48:49], v[44:45]
	v_mov_b64_e32 v[52:53], v[40:41]
	v_mov_b64_e32 v[56:57], v[32:33]
	s_cmp_ge_u32 s8, s11
	v_mov_b64_e32 v[60:61], v[36:37]
	s_cbranch_scc1 .LBB0_1223
	s_add_i32 s8, s10, 0x200
	s_cmp_lt_u32 s3, 6
	s_cselect_b32 s8, s8, s18
	s_ashr_i32 s9, s8, 31
	s_lshl_b64 s[8:9], s[8:9], 12
	v_lshl_add_u64 v[44:45], v[154:155], 0, s[8:9]
	global_load_dwordx4 v[36:39], v[44:45], off
	global_load_dwordx4 v[32:35], v[44:45], off offset:1024
	global_load_dwordx4 v[40:43], v[44:45], off offset:2048
	s_nop 0
	global_load_dwordx4 v[44:47], v[44:45], off offset:3072

.LBB0_1434:
	s_or_b64 exec, exec, s[6:7]
	s_mov_b64 s[6:7], -1
	s_and_b64 vcc, exec, s[0:1]
	s_waitcnt lgkmcnt(0)
	s_barrier
	s_cbranch_vccz .LBB0_1467
	v_mov_b32_e32 v0, v196
	v_readlane_b32 s8, v253, 27
	v_readlane_b32 s10, v253, 29
	v_readlane_b32 s11, v253, 30
	v_and_b32_e32 v37, 63, v0
	v_readfirstlane_b32 s6, v0
	v_mov_b32_e32 v0, s10
	v_mov_b32_e32 v1, s11
	v_readlane_b32 s9, v253, 28
	v_readfirstlane_b32 s12, v0
	v_readfirstlane_b32 s13, v1
	v_mov_b32_e32 v0, s94
	v_mov_b32_e32 v1, s95
	v_readlane_b32 s10, v255, 7
	v_readfirstlane_b32 s8, v0
	v_readfirstlane_b32 s9, v1
	s_add_u32 s3, s8, 0x300000
	v_readlane_b32 s14, v255, 11
	s_addc_u32 s20, s9, 0
	v_lshlrev_b32_e32 v144, 4, v37
	v_readlane_b32 s11, v255, 8
	v_readlane_b32 s15, v255, 12
	s_ashr_i32 s6, s6, 6
	v_readlane_b32 s7, v253, 53
	s_nop 1
	global_load_dwordx4 v[0:3], v144, s[10:11]
	global_load_dwordx4 v[4:7], v144, s[10:11] offset:1024
	global_load_dwordx4 v[8:11], v144, s[14:15]
	global_load_dwordx4 v[12:15], v144, s[14:15] offset:1024
	global_load_dwordx4 v[16:19], v144, s[10:11] offset:2048
	global_load_dwordx4 v[20:23], v144, s[10:11] offset:3072
	global_load_dwordx4 v[24:27], v144, s[14:15] offset:2048
	global_load_dwordx4 v[28:31], v144, s[14:15] offset:3072
	s_add_i32 s14, s7, s6
	s_ashr_i32 s15, s14, 31
	s_add_i32 s24, s6, s88
	s_lshl_b64 s[6:7], s[14:15], 12
	s_add_u32 s6, s12, s6
	s_addc_u32 s7, s13, s7
	v_lshl_add_u64 v[32:33], s[6:7], 0, v[144:145]
	global_load_dwordx4 v[100:103], v144, s[6:7]
	global_load_dwordx4 v[104:107], v144, s[6:7] offset:1024
	global_load_dwordx4 v[108:111], v144, s[6:7] offset:2048
	global_load_dwordx4 v[96:99], v144, s[6:7] offset:3072
	s_mov_b64 s[6:7], 0x100000
	v_lshl_add_u64 v[34:35], v[32:33], 0, s[6:7]
	s_mov_b32 s6, 0x100000
	v_add_co_u32_e32 v32, vcc, s6, v32
	s_add_u32 s15, s8, 0x6300000
	s_nop 0
	v_addc_co_u32_e32 v33, vcc, 0, v33, vcc
	global_load_dwordx4 v[84:87], v[34:35], off offset:1024
	global_load_dwordx4 v[88:91], v[34:35], off offset:2048
	global_load_dwordx4 v[80:83], v[32:33], off
	global_load_dwordx4 v[92:95], v[34:35], off offset:3072
	v_and_b32_e32 v35, 64, v220
	v_xor_b32_e32 v33, 16, v220
	v_add_u32_e32 v35, 64, v35
	s_addc_u32 s21, s9, 0
	v_cmp_lt_i32_e32 vcc, v33, v35
	s_cmpk_lt_i32 s24, 0x200
	s_cselect_b32 s23, 9, 8
	v_cndmask_b32_e32 v33, v220, v33, vcc
	s_addk_i32 s24, 0x4000
	v_lshlrev_b32_e32 v121, 2, v33
	v_xor_b32_e32 v33, 32, v220
	v_lshlrev_b32_e32 v120, 2, v37
	v_cmp_lt_i32_e32 vcc, v33, v35
	s_add_u32 s25, s8, 0x280000
	v_or_b32_e32 v32, 0x100, v120
	v_or_b32_e32 v34, 0x200, v120
	v_or_b32_e32 v36, 0x300, v120
	v_cndmask_b32_e32 v33, v220, v33, vcc
	s_addc_u32 s26, s9, 0
	v_lshl_add_u64 v[38:39], s[8:9], 0, v[144:145]
	s_mov_b64 s[8:9], 0x10800000
	s_mov_b32 s22, 0
	v_lshlrev_b32_e32 v128, 2, v33
	v_cmp_eq_u32_e64 s[6:7], 0, v37
	v_lshl_add_u64 v[122:123], s[12:13], 0, v[144:145]
	v_lshl_add_u64 v[124:125], v[38:39], 0, s[8:9]
	v_lshlrev_b32_e32 v129, 2, v32
	v_lshlrev_b32_e32 v130, 2, v34
	v_lshlrev_b32_e32 v131, 2, v36
	s_waitcnt vmcnt(0)
	s_branch .LBB0_1437

.LBB0_1437:
	s_lshl_b32 s8, s22, 8
	s_add_i32 s8, s8, s14
	s_waitcnt vmcnt(5)
	v_mov_b64_e32 v[76:77], v[80:81]
	s_cmp_lt_u32 s22, 8
	s_waitcnt vmcnt(4)
	v_mov_b64_e32 v[48:49], v[92:93]
	v_mov_b64_e32 v[56:57], v[88:89]
	v_mov_b64_e32 v[68:69], v[84:85]
	v_mov_b64_e32 v[78:79], v[82:83]
	s_cselect_b32 s16, s8, s24
	v_cndmask_b32_e64 v80, 0, 1, s[4:5]
	v_mov_b64_e32 v[50:51], v[94:95]
	v_mov_b64_e32 v[58:59], v[90:91]
	v_mov_b64_e32 v[70:71], v[86:87]
	s_ashr_i32 s17, s16, 31
	s_add_i32 s92, s16, 0xffffc000
	v_cmp_ne_u32_e64 s[8:9], 1, v80
	s_andn2_b64 vcc, exec, s[4:5]
	v_lshlrev_b32_e32 v132, 2, v120
	s_cbranch_vccnz .LBB0_1439
	s_lshr_b32 s11, s92, 2
	s_ashr_i32 s10, s16, 11
	s_add_i32 s11, s11, 8
	s_cmpk_lt_i32 s16, 0x4000
	s_cselect_b32 s10, s10, s11
	s_addk_i32 s10, 0x88
	s_mul_hi_i32 s11, s10, 0x9000
	s_mul_i32 s10, s10, 0x9000
	s_add_u32 s10, s3, s10
	s_addc_u32 s11, s20, s11
	s_add_u32 s18, s10, 0x1000
	s_addc_u32 s19, s11, 0
	global_load_dwordx4 v[40:43], v132, s[10:11] offset:1024
	global_load_dwordx4 v[52:55], v132, s[10:11] offset:2048
	global_load_dwordx4 v[32:35], v129, s[18:19]
	global_load_dwordx4 v[44:47], v130, s[18:19]
	global_load_dwordx4 v[36:39], v132, s[18:19]
	global_load_dwordx4 v[72:75], v132, s[10:11] offset:3072
	global_load_dwordx4 v[64:67], v132, s[10:11]
	global_load_dwordx4 v[60:63], v131, s[18:19]

.LBB0_1467:
	s_and_b64 vcc, exec, s[6:7]
	s_cbranch_vccz .LBB0_1489
	v_mov_b32_e32 v0, v196
	v_readlane_b32 s8, v253, 27
	v_readlane_b32 s9, v253, 28
	v_readlane_b32 s10, v253, 29
	v_readlane_b32 s11, v253, 30
	v_and_b32_e32 v49, 63, v0
	v_readfirstlane_b32 s3, v0
	v_mov_b32_e32 v0, s10
	v_mov_b32_e32 v1, s11
	v_readlane_b32 s6, v255, 5
	v_readlane_b32 s8, v255, 9
	v_mov_b32_e32 v48, s94
	v_mov_b32_e32 v50, s95
	v_lshlrev_b32_e32 v144, 4, v49
	v_readlane_b32 s7, v255, 6
	v_readlane_b32 s9, v255, 10
	v_readfirstlane_b32 s10, v0
	v_readfirstlane_b32 s11, v1
	s_nop 1
	global_load_dwordx4 v[0:3], v144, s[6:7]
	global_load_dwordx4 v[4:7], v144, s[6:7] offset:1024
	global_load_dwordx4 v[8:11], v144, s[8:9]
	global_load_dwordx4 v[12:15], v144, s[8:9] offset:1024
	global_load_dwordx4 v[16:19], v144, s[6:7] offset:2048
	global_load_dwordx4 v[20:23], v144, s[6:7] offset:3072
	global_load_dwordx4 v[24:27], v144, s[8:9] offset:2048
	global_load_dwordx4 v[28:31], v144, s[8:9] offset:3072
	s_ashr_i32 s3, s3, 6
	v_readlane_b32 s6, v253, 53
	s_add_i32 s12, s6, s3
	s_ashr_i32 s13, s12, 31
	s_add_i32 s20, s3, s88
	s_lshl_b64 s[6:7], s[12:13], 12
	s_add_u32 s6, s10, s6
	s_addc_u32 s7, s11, s7
	s_waitcnt vmcnt(13)
	v_lshl_add_u64 v[32:33], s[6:7], 0, v[144:145]
	s_mov_b32 s3, 0x100000
	global_load_dwordx4 v[100:103], v144, s[6:7]
	global_load_dwordx4 v[104:107], v144, s[6:7] offset:1024
	global_load_dwordx4 v[108:111], v144, s[6:7] offset:2048
	global_load_dwordx4 v[88:91], v144, s[6:7] offset:3072
	s_mov_b64 s[6:7], 0x100000
	s_waitcnt vmcnt(15)
	v_add_co_u32_e32 v36, vcc, s3, v32
	v_lshl_add_u64 v[44:45], v[32:33], 0, s[6:7]
	s_nop 0
	v_addc_co_u32_e32 v37, vcc, 0, v33, vcc
	global_load_dwordx4 v[32:35], v[44:45], off offset:1024
	global_load_dwordx4 v[40:43], v[44:45], off offset:2048
	s_nop 0
	global_load_dwordx4 v[36:39], v[36:37], off
	s_nop 0
	global_load_dwordx4 v[44:47], v[44:45], off offset:3072
	v_and_b32_e32 v53, 64, v220
	s_cmpk_lt_i32 s20, 0x200
	v_xor_b32_e32 v51, 16, v220
	v_add_u32_e32 v53, 64, v53
	v_readfirstlane_b32 s8, v48
	s_cselect_b32 s13, 9, 8
	s_addk_i32 s20, 0x4000
	v_cmp_lt_i32_e32 vcc, v51, v53
	v_readfirstlane_b32 s9, v50
	s_add_u32 s21, s8, 0x303000
	v_cndmask_b32_e32 v51, v220, v51, vcc
	s_addc_u32 s22, s9, 0
	v_lshlrev_b32_e32 v128, 2, v51
	v_xor_b32_e32 v51, 32, v220
	v_lshlrev_b32_e32 v56, 3, v49
	v_mov_b32_e32 v57, v145
	v_lshlrev_b32_e32 v48, 2, v49
	v_cmp_lt_i32_e32 vcc, v51, v53
	s_add_u32 s23, s8, 0x280000
	v_lshl_add_u64 v[56:57], s[8:9], 0, v[56:57]
	s_mov_b64 s[14:15], 0x6300000
	v_or_b32_e32 v50, 0x100, v48
	v_or_b32_e32 v52, 0x200, v48
	v_or_b32_e32 v54, 0x300, v48
	v_cndmask_b32_e32 v51, v220, v51, vcc
	s_addc_u32 s24, s9, 0
	v_lshl_add_u64 v[122:123], v[56:57], 0, s[14:15]
	v_lshl_add_u64 v[56:57], s[8:9], 0, v[144:145]
	s_mov_b64 s[8:9], 0x10800000
	s_mov_b32 s3, 0
	v_lshlrev_b32_e32 v129, 2, v51
	v_cmp_eq_u32_e64 s[6:7], 0, v49
	v_lshl_add_u64 v[120:121], s[10:11], 0, v[144:145]
	v_lshl_add_u64 v[124:125], v[56:57], 0, s[8:9]
	v_lshlrev_b32_e32 v130, 2, v48
	v_lshlrev_b32_e32 v131, 2, v50
	v_lshlrev_b32_e32 v132, 2, v52
	v_lshlrev_b32_e32 v133, 2, v54
	s_waitcnt vmcnt(0)
	s_branch .LBB0_1470

.LBB0_1470:
	s_lshl_b32 s8, s3, 8
	s_add_i32 s8, s8, s12
	s_cmp_lt_u32 s3, 8
	s_cselect_b32 s14, s8, s20
	s_add_i32 s92, s14, 0xffffc000
	s_lshr_b32 s9, s92, 2
	s_ashr_i32 s8, s14, 11
	s_add_i32 s9, s9, 8
	s_cmpk_lt_i32 s14, 0x4000
	s_cselect_b32 s8, s8, s9
	v_readlane_b32 s9, v255, 4
	s_add_i32 s8, s8, s9
	s_mul_hi_i32 s9, s8, 0x9000
	s_mul_i32 s8, s8, 0x9000
	s_add_u32 s8, s21, s8
	s_addc_u32 s9, s22, s9
	s_add_u32 s16, s8, 0x1000
	s_addc_u32 s17, s9, 0
	global_load_dwordx4 v[92:95], v130, s[8:9]
	global_load_dwordx4 v[80:83], v130, s[8:9] offset:1024
	global_load_dwordx4 v[96:99], v130, s[16:17]
	global_load_dwordx4 v[84:87], v131, s[16:17]
	global_load_dwordx4 v[72:75], v130, s[8:9] offset:2048
	global_load_dwordx4 v[64:67], v130, s[8:9] offset:3072
	global_load_dwordx4 v[76:79], v132, s[16:17]
	global_load_dwordx4 v[68:71], v133, s[16:17]
	s_waitcnt vmcnt(12)
	v_mov_b64_e32 v[50:51], v[46:47]
	v_mov_b64_e32 v[54:55], v[42:43]
	v_mov_b64_e32 v[58:59], v[34:35]
	s_add_i32 s8, s3, 2
	v_mov_b64_e32 v[62:63], v[38:39]
	v_mov_b64_e32 v[48:49], v[44:45]
	v_mov_b64_e32 v[52:53], v[40:41]
	v_mov_b64_e32 v[56:57], v[32:33]
	s_cmp_ge_u32 s8, s13
	v_mov_b64_e32 v[60:61], v[36:37]
	s_cbranch_scc1 .LBB0_1472
	s_lshl_b32 s8, s8, 8
	s_add_i32 s8, s8, s12
	s_cmp_lt_u32 s3, 6
	s_cselect_b32 s8, s8, s20
	s_ashr_i32 s9, s8, 31
	s_lshl_b64 s[8:9], s[8:9], 12
	v_lshl_add_u64 v[44:45], v[120:121], 0, s[8:9]
	global_load_dwordx4 v[36:39], v[44:45], off
	global_load_dwordx4 v[32:35], v[44:45], off offset:1024
	global_load_dwordx4 v[40:43], v[44:45], off offset:2048
	s_nop 0
	global_load_dwordx4 v[44:47], v[44:45], off offset:3072
